# weight-tile L2 warm-up also before W_in, FFN-up 1..3 and QK (seams after the first)
# baseline (speedup 1.0000x reference)
; __device__ __forceinline__ void xcd_barrier(const XcdBarrier& b) {
;     asm volatile("s_waitcnt vmcnt(0)" ::: "memory");
;     __syncthreads();
; __global__ void __launch_bounds__(NTHREADS, 2) mega_fwd(Args a) {
;     ...
;     if (IN(3)) { BUILD_RTAB(RT, T, 1536, false, 1) EpiWin E{VC, US, RT}; run_gemm(lds, XB, (const bf16_t*)(ws + WS_WIN), T, 1536, D, E); }
.LBB0_332:
	s_cmp_gt_i32 s31, 3
	s_cselect_b64 s[0:1], -1, 0
	s_and_b64 s[4:5], s[8:9], s[0:1]
	s_andn2_b64 vcc, exec, s[4:5]
	s_cbranch_vccnz .LBB0_386
	s_waitcnt vmcnt(0)
	s_waitcnt vmcnt(0) lgkmcnt(0)
	s_barrier
	v_readlane_b32 s100, v249, 18
	s_nop 3
	s_cmp_eq_u32 s100, 0
	s_cbranch_scc1 .Lwarmb_done_0
	s_lshr_b32 s101, s92, 9
	s_and_b32 s101, s101, 3
	s_mul_i32 s101, s101, 0x80000
	s_add_u32 s98, s28, 0x4a00000
	s_addc_u32 s99, s29, 0
	s_add_u32 s98, s98, s101
	s_addc_u32 s99, s99, 0
	v_lshrrev_b32_e32 v250, 1, v196
	v_lshl_add_u32 v250, s100, 5, v250
	v_mul_u32_u24_e32 v250, 0x800, v250
	v_and_b32_e32 v251, 1, v196
	v_lshl_add_u32 v250, v251, 7, v250
	global_load_dword v250, v250, s[98:99]

; __device__ __forceinline__ unsigned xb_ld(unsigned* p)              { return __hip_atomic_load(p, __ATOMIC_RELAXED, __HIP_MEMORY_SCOPE_AGENT); }
; __device__ __forceinline__ void xcd_barrier_complete(unsigned* bar, unsigned x, unsigned& nloc, unsigned& nx) {
;     const unsigned G = gridDim.x * gridDim.y * gridDim.z;
;     unsigned sum, cnt, mine, sp = 0u;
;     for (;;) {
;         sum = 0u; cnt = 0u; mine = 0u;
; #pragma unroll
;         for (unsigned j = 0; j < 16; ++j) { const unsigned c = xb_ld(&bar[XB_XCNT(j)]); sum += c; cnt += (c > 0u) ? 1u : 0u; mine = (j == x) ? c : mine; }
; __device__ __forceinline__ void xcd_barrier(const XcdBarrier& b) {
;     asm volatile("s_waitcnt vmcnt(0)" ::: "memory");
;     __syncthreads();
;     if (threadIdx.x == 0) {
;         unsigned* bar = b.bar;
;         __builtin_amdgcn_s_waitcnt(0);
;         unsigned nloc = b.st[0], nx = b.st[1];
;         if (nloc == 0u) { xcd_barrier_complete(bar, b.x, nloc, nx); b.st[0] = nloc; b.st[1] = nx; }
.LBB0_728:
	s_cmp_gt_i32 s31, 8
	s_cselect_b64 s[4:5], -1, 0
	s_and_b64 s[0:1], s[0:1], s[4:5]
	s_andn2_b64 vcc, exec, s[0:1]
	s_cbranch_vccnz .LBB0_782
	s_waitcnt vmcnt(0)
	s_waitcnt vmcnt(0) lgkmcnt(0)
	s_barrier
	v_readlane_b32 s100, v249, 18
	s_nop 3
	s_cmp_eq_u32 s100, 0
	s_cbranch_scc1 .Lwarmb_done_1
	s_lshr_b32 s101, s92, 9
	s_and_b32 s101, s101, 3
	s_mul_i32 s101, s101, 0x80000
	s_add_u32 s98, s28, 0x1300000
	s_addc_u32 s99, s29, 0
	s_add_u32 s98, s98, s101
	s_addc_u32 s99, s99, 0
	v_lshrrev_b32_e32 v250, 1, v196
	v_lshl_add_u32 v250, s100, 5, v250
	v_mul_u32_u24_e32 v250, 0x800, v250
	v_and_b32_e32 v251, 1, v196
	v_lshl_add_u32 v250, v251, 7, v250
	global_load_dword v250, v250, s[98:99]
.Lwarmb_done_1:
	s_and_saveexec_b64 s[0:1], s[80:81]
	s_cbranch_execz .LBB0_781
	buffer_inv sc1
	s_add_i32 s3, 0, 0x23fc0
	v_mov_b32_e32 v0, s3
	s_waitcnt vmcnt(0) expcnt(0) lgkmcnt(0)
	ds_read_b32 v2, v0
	s_add_i32 s3, 0, 0x23fc4
	v_mov_b32_e32 v0, s3
	ds_read_b32 v0, v0
	s_waitcnt lgkmcnt(1)
	v_cmp_ne_u32_e32 vcc, 0, v2
	s_cbranch_vccnz .LBB0_745
	s_add_u32 s6, s28, 0x180200
	s_addc_u32 s7, s29, 0
	s_add_u32 s8, s28, 0x180400
	s_addc_u32 s9, s29, 0
	s_add_u32 s10, s28, 0x180500
	s_addc_u32 s11, s29, 0
	s_add_u32 s12, s28, 0x180600
	s_addc_u32 s13, s29, 0
	s_add_u32 s14, s28, 0x180700
	s_addc_u32 s15, s29, 0
	s_add_u32 s16, s28, 0x180800
	s_addc_u32 s17, s29, 0
	s_add_u32 s18, s28, 0x180900
	s_addc_u32 s19, s29, 0
	s_add_u32 s20, s28, 0x180a00
	s_addc_u32 s21, s29, 0
	s_add_u32 s34, s28, 0x180b00
	s_addc_u32 s35, s29, 0
	s_add_u32 s38, s28, 0x180c00
	s_addc_u32 s39, s29, 0
	s_add_u32 s44, s28, 0x180d00
	s_addc_u32 s45, s29, 0
	s_add_u32 s46, s28, 0x180e00
	s_addc_u32 s47, s29, 0
	s_add_u32 s48, s28, 0x180f00
	s_addc_u32 s49, s29, 0
	s_add_u32 s50, s28, 0x181000
	s_addc_u32 s51, s29, 0
	s_add_u32 s52, s28, 0x181100
	s_addc_u32 s53, s29, 0
	s_add_u32 s54, s28, 0x181200
	s_addc_u32 s55, s29, 0
	s_mul_i32 s3, s23, s96
	s_add_u32 s56, s28, 0x181300
	s_mul_i32 s3, s3, s22
	s_addc_u32 s57, s29, 0
	s_mov_b32 s33, 1
	v_mov_b32_e32 v16, 0
	s_branch .LBB0_733

; __device__ __forceinline__ void xcd_barrier(const XcdBarrier& b) {
;     asm volatile("s_waitcnt vmcnt(0)" ::: "memory");
;     __syncthreads();
.LBB0_918:
	s_cmp_gt_i32 s31, 10
	s_cselect_b64 s[0:1], -1, 0
	s_and_b64 s[4:5], s[8:9], s[0:1]
	s_andn2_b64 vcc, exec, s[4:5]
	s_cbranch_vccnz .LBB0_972
	s_waitcnt vmcnt(0)
	s_waitcnt vmcnt(0) lgkmcnt(0)
	s_barrier
	v_readlane_b32 s100, v249, 18
	s_nop 3
	s_cmp_eq_u32 s100, 0
	s_cbranch_scc1 .Lwarmb_done_2
	s_lshr_b32 s101, s92, 9
	s_and_b32 s101, s101, 3
	s_mul_i32 s101, s101, 0x80000
	s_add_u32 s98, s28, 0x1e00000
	s_addc_u32 s99, s29, 0
	s_add_u32 s98, s98, s101
	s_addc_u32 s99, s99, 0
	v_lshrrev_b32_e32 v250, 1, v196
	v_lshl_add_u32 v250, s100, 5, v250
	v_mul_u32_u24_e32 v250, 0x800, v250
	v_and_b32_e32 v251, 1, v196
	v_lshl_add_u32 v250, v251, 7, v250
	global_load_dword v250, v250, s[98:99]

; __device__ __forceinline__ void xcd_barrier(const XcdBarrier& b) {
;     asm volatile("s_waitcnt vmcnt(0)" ::: "memory");
;     __syncthreads();
.LBB0_1108:
	s_cmp_gt_i32 s31, 12
	s_cselect_b64 s[0:1], -1, 0
	s_and_b64 s[4:5], s[8:9], s[0:1]
	s_andn2_b64 vcc, exec, s[4:5]
	s_cbranch_vccnz .LBB0_1162
	s_waitcnt vmcnt(0)
	s_waitcnt vmcnt(0) lgkmcnt(0)
	s_barrier
	v_readlane_b32 s100, v249, 18
	s_nop 3
	s_cmp_eq_u32 s100, 0
	s_cbranch_scc1 .Lwarmb_done_3
	s_lshr_b32 s101, s92, 9
	s_and_b32 s101, s101, 3
	s_mul_i32 s101, s101, 0x80000
	s_add_u32 s98, s28, 0x5000000
	s_addc_u32 s99, s29, 0
	s_add_u32 s98, s98, s101
	s_addc_u32 s99, s99, 0
	v_lshrrev_b32_e32 v250, 1, v196
	v_lshl_add_u32 v250, s100, 5, v250
	v_mul_u32_u24_e32 v250, 0x800, v250
	v_and_b32_e32 v251, 1, v196
	v_lshl_add_u32 v250, v251, 7, v250
	global_load_dword v250, v250, s[98:99]

; __device__ __forceinline__ unsigned xb_ld(unsigned* p)              { return __hip_atomic_load(p, __ATOMIC_RELAXED, __HIP_MEMORY_SCOPE_AGENT); }
; __device__ __forceinline__ void xcd_barrier_complete(unsigned* bar, unsigned x, unsigned& nloc, unsigned& nx) {
;     const unsigned G = gridDim.x * gridDim.y * gridDim.z;
;     unsigned sum, cnt, mine, sp = 0u;
;     for (;;) {
;         sum = 0u; cnt = 0u; mine = 0u;
; #pragma unroll
;         for (unsigned j = 0; j < 16; ++j) { const unsigned c = xb_ld(&bar[XB_XCNT(j)]); sum += c; cnt += (c > 0u) ? 1u : 0u; mine = (j == x) ? c : mine; }
; __device__ __forceinline__ void xcd_barrier(const XcdBarrier& b) {
;     asm volatile("s_waitcnt vmcnt(0)" ::: "memory");
;     __syncthreads();
;     if (threadIdx.x == 0) {
;         unsigned* bar = b.bar;
;         __builtin_amdgcn_s_waitcnt(0);
;         unsigned nloc = b.st[0], nx = b.st[1];
;         if (nloc == 0u) { xcd_barrier_complete(bar, b.x, nloc, nx); b.st[0] = nloc; b.st[1] = nx; }
.LBB0_1658:
	s_cmp_gt_i32 s31, 16
	s_cselect_b64 s[4:5], -1, 0
	s_and_b64 s[0:1], s[0:1], s[4:5]
	s_andn2_b64 vcc, exec, s[0:1]
	s_cbranch_vccnz .LBB0_1712
	s_waitcnt vmcnt(0)
	s_waitcnt vmcnt(0) lgkmcnt(0)
	s_barrier
	v_readlane_b32 s100, v249, 18
	s_nop 3
	s_cmp_eq_u32 s100, 0
	s_cbranch_scc1 .Lwarmb_done_4
	s_lshr_b32 s101, s92, 9
	s_and_b32 s101, s101, 3
	s_mul_i32 s101, s101, 0x80000
	s_add_u32 s98, s28, 0x2900000
	s_addc_u32 s99, s29, 0
	s_add_u32 s98, s98, s101
	s_addc_u32 s99, s99, 0
	v_lshrrev_b32_e32 v250, 1, v196
	v_lshl_add_u32 v250, s100, 5, v250
	v_mul_u32_u24_e32 v250, 0x800, v250
	v_and_b32_e32 v251, 1, v196
	v_lshl_add_u32 v250, v251, 7, v250
	global_load_dword v250, v250, s[98:99]
.Lwarmb_done_4:
	s_and_saveexec_b64 s[0:1], s[80:81]
	s_cbranch_execz .LBB0_1711
	buffer_inv sc1
	s_add_i32 s3, 0, 0x23fc0
	v_mov_b32_e32 v0, s3
	s_waitcnt vmcnt(0) expcnt(0) lgkmcnt(0)
	ds_read_b32 v2, v0
	s_add_i32 s3, 0, 0x23fc4
	v_mov_b32_e32 v0, s3
	ds_read_b32 v0, v0
	s_waitcnt lgkmcnt(1)
	v_cmp_ne_u32_e32 vcc, 0, v2
	s_cbranch_vccnz .LBB0_1675
	s_add_u32 s6, s28, 0x180200
	s_addc_u32 s7, s29, 0
	s_add_u32 s8, s28, 0x180400
	s_addc_u32 s9, s29, 0
	s_add_u32 s10, s28, 0x180500
	s_addc_u32 s11, s29, 0
	s_add_u32 s12, s28, 0x180600
	s_addc_u32 s13, s29, 0
	s_add_u32 s14, s28, 0x180700
	s_addc_u32 s15, s29, 0
	s_add_u32 s16, s28, 0x180800
	s_addc_u32 s17, s29, 0
	s_add_u32 s18, s28, 0x180900
	s_addc_u32 s19, s29, 0
	s_add_u32 s20, s28, 0x180a00
	s_addc_u32 s21, s29, 0
	s_add_u32 s34, s28, 0x180b00
	s_addc_u32 s35, s29, 0
	s_add_u32 s38, s28, 0x180c00
	s_addc_u32 s39, s29, 0
	s_add_u32 s42, s28, 0x180d00
	s_addc_u32 s43, s29, 0
	s_add_u32 s44, s28, 0x180e00
	s_addc_u32 s45, s29, 0
	s_add_u32 s46, s28, 0x180f00
	s_addc_u32 s47, s29, 0
	s_add_u32 s48, s28, 0x181000
	s_addc_u32 s49, s29, 0
	s_add_u32 s50, s28, 0x181100
	s_addc_u32 s51, s29, 0
	s_add_u32 s52, s28, 0x181200
	s_addc_u32 s53, s29, 0
	s_mul_i32 s3, s23, s96
	s_add_u32 s54, s28, 0x181300
	s_mul_i32 s3, s3, s22
	s_addc_u32 s55, s29, 0
	s_mov_b32 s33, 1
	v_mov_b32_e32 v16, 0
	s_branch .LBB0_1663
